# pair barrier pollers sleep 32 (2048 cycles) between polls
# baseline (speedup 1.0000x reference)
.Lgb_pair_244:
	global_load_dword v3, v2, s[12:13] sc1
	s_waitcnt vmcnt(0)
	v_readfirstlane_b32 s4, v3
	s_nop 3
	s_cmp_ge_u32 s4, s16
	s_cbranch_scc1 .Lgb_pair_ok_244
	s_sleep 32
	s_add_i32 s1, s1, 1
	s_cmp_lt_u32 s1, 0x40000
	s_cbranch_scc1 .Lgb_pair_244
